# instruction trim: removed the two redundant s_nop 3 after the MLA inline LDS-store blocks (on top of v27)
# baseline (speedup 1.0000x reference)
; template <bool MLA, int DK, int DV>
; __device__ __forceinline__ void attn_core(const Params& p, int b, int h, int map, int q0, int nt, char* smem,
;                                           f32x16 (&o)[DV / 32], float& lout) {
;     ...
;           const float x_ = __builtin_amdgcn_exp2f(fmaf(cur_[e_ >> 4][e_ & 15], sc, -mrun));
;           cur_[e_ >> 4][e_ & 15] = x_; psum += x_;
;         }
;       }
;       __builtin_amdgcn_sched_group_barrier(0x100, NM, 0);
; #pragma unroll
;       for (int j = 0; j < NM; ++j) {
;         __builtin_amdgcn_sched_group_barrier(0x008, 1, 0);
;         __builtin_amdgcn_sched_group_barrier(0x002, 96 / NM, 0);
;       }
;     } else {
; #pragma unroll
;       for (int sub = 0; sub < 2; ++sub)
; #pragma unroll
;         for (int i = 0; i < 16; ++i) { const float x_ = __builtin_amdgcn_exp2f(fmaf(cur_[sub][i], sc, -mrun)); cur_[sub][i] = x_; psum += x_; }
;     }
;     lrun += psum;
;     bf16x8 pb[4];
; #pragma unroll
;     for (int kb = 0; kb < 4; ++kb) {
;       const int sub = kb >> 1, s8 = (kb & 1) * 8;
;       u32x4 pk;
;       pk.x = pack2(cur_[sub][s8 + 0], cur_[sub][s8 + 1]);
;       pk.y = pack2(cur_[sub][s8 + 2], cur_[sub][s8 + 3]);
;       pk.z = pack2(cur_[sub][s8 + 4], cur_[sub][s8 + 5]);
;       pk.w = pack2(cur_[sub][s8 + 6], cur_[sub][s8 + 7]);
;       pb[kb] = __builtin_bit_cast(bf16x8, pk);
;     }
;     float mx = -INFINITY;
; #pragma unroll
;     for (int hb = 0; hb < 2; ++hb) {
;       bf16x8 vf[2][NDVT];
; #pragma unroll
;       for (int q = 0; q < 2; ++q)
; #pragma unroll
;         for (int d = 0; d < NDVT; ++d) {
;           const bft* vp = Vc + (d * 32 + r) * VS_STRIDE + (hb * 2 + q) * 16 + 4 * h2;
;           const u32x2 lo = *(const u32x2*)vp, hi = *(const u32x2*)(vp + 8);
;           const u32x4 pa4 = {lo.x, lo.y, hi.x, hi.y};
;           vf[q][d] = __builtin_bit_cast(bf16x8, pa4);
;         }
; #pragma unroll
;       for (int q = 0; q < 2; ++q) {
;         const int kb = hb * 2 + q;
; #pragma unroll
;         for (int d = 0; d < NDVT; ++d) o[d] = MFMA32(vf[q][d], pb[kb], o[d]);
; #pragma unroll
;         for (int i = 0; i < 8; ++i) mx = fmaxf(mx, nxt_[kb >> 1][(kb & 1) * 8 + i]);
;       }
;     }
;     if (has1) {
;       mx *= sc;
;       if (__any(mx > mrun + 12.f)) {
;         mx = fmaxf(mx, __shfl_xor(mx, 32));
;         const float mnew = fmaxf(mrun, mx);
.Lm1i_d:
	s_or_b64 exec, exec, s[74:75]
	ds_read2_b64 v[202:205], v245 offset0:36 offset1:38
	v_exp_f32_e32 v65, v65
	v_exp_f32_e32 v66, v66
	s_waitcnt lgkmcnt(5)
	v_mfma_f32_32x32x16_bf16 v[80:95], v[248:251], v[112:115], v[80:95]
	ds_read2_b64 v[248:251], v244 offset0:8 offset1:10
	v_exp_f32_e32 v67, v67
	v_add_f32_e32 v163, v64, v163
	v_add_f32_e32 v210, v65, v210
	s_waitcnt lgkmcnt(5)
	v_mfma_f32_32x32x16_bf16 v[80:95], v[216:219], v[116:119], v[80:95]
	ds_read2_b64 v[216:219], v245 offset0:40 offset1:42
	v_add_f32_e32 v163, v66, v163
	v_add_f32_e32 v210, v67, v210
	v_exp_f32_e32 v68, v68
	v_exp_f32_e32 v69, v69
	s_waitcnt lgkmcnt(5)
	v_mfma_f32_32x32x16_bf16 v[32:47], v[132:135], v[180:183], v[32:47]
	ds_read2_b64 v[132:135], v244 offset0:12 offset1:14
	v_exp_f32_e32 v70, v70
	v_exp_f32_e32 v71, v71
	s_waitcnt lgkmcnt(5)
	v_mfma_f32_32x32x16_bf16 v[0:15], v[136:139], v[180:183], v[0:15]
	ds_read2_b64 v[136:139], v245 offset0:44 offset1:46
	v_add_f32_e32 v163, v68, v163
	v_add_f32_e32 v210, v69, v210
	v_add_f32_e32 v163, v70, v163
	v_add_f32_e32 v210, v71, v210
	v_cvt_pk_bf16_f32 v188, v64, v65
	s_waitcnt lgkmcnt(5)
	v_mfma_f32_32x32x16_bf16 v[32:47], v[198:201], v[184:187], v[32:47]
	v_cvt_pk_bf16_f32 v189, v66, v67
	v_cvt_pk_bf16_f32 v190, v68, v69
	v_cvt_pk_bf16_f32 v191, v70, v71
	v_exp_f32_e32 v72, v72
	s_waitcnt lgkmcnt(4)
	v_mfma_f32_32x32x16_bf16 v[0:15], v[202:205], v[184:187], v[0:15]
	v_exp_f32_e32 v73, v73
	v_exp_f32_e32 v74, v74
	v_exp_f32_e32 v75, v75
	s_waitcnt lgkmcnt(3)
	v_mfma_f32_32x32x16_bf16 v[32:47], v[248:251], v[188:191], v[32:47]
	v_add_f32_e32 v163, v72, v163
	v_add_f32_e32 v210, v73, v210
	v_add_f32_e32 v163, v74, v163
	v_add_f32_e32 v210, v75, v210
	s_waitcnt lgkmcnt(2)
	v_mfma_f32_32x32x16_bf16 v[0:15], v[216:219], v[188:191], v[0:15]
	v_exp_f32_e32 v76, v76
	v_exp_f32_e32 v77, v77
	v_exp_f32_e32 v78, v78
	v_exp_f32_e32 v79, v79
	v_add_f32_e32 v163, v76, v163
	v_add_f32_e32 v210, v77, v210
	v_add_f32_e32 v163, v78, v163
	v_add_f32_e32 v210, v79, v210
	v_cvt_pk_bf16_f32 v192, v72, v73
	v_cvt_pk_bf16_f32 v193, v74, v75
	v_cvt_pk_bf16_f32 v194, v76, v77
	v_cvt_pk_bf16_f32 v195, v78, v79
	s_waitcnt lgkmcnt(1)
	s_nop 0
	v_mfma_f32_32x32x16_bf16 v[32:47], v[132:135], v[192:195], v[32:47]
	s_waitcnt lgkmcnt(0)
	v_mfma_f32_32x32x16_bf16 v[0:15], v[136:139], v[192:195], v[0:15]
	v_add_f32_e32 v163, v163, v210
	v_add_f32_e32 v149, v149, v163
	s_andn2_b64 s[16:17], exec, s[70:71]
	v_cmp_lt_f32_e32 vcc, 0x45800000, v163
	s_cbranch_vccz .Lmla1_post
	v_max3_f32 v163, v16, v17, v18
	v_max3_f32 v163, v163, v19, v20
	v_max3_f32 v163, v163, v21, v22
	v_max3_f32 v163, v163, v23, v24
	v_max3_f32 v163, v163, v25, v26
	v_max3_f32 v163, v163, v27, v28
	v_max3_f32 v163, v163, v29, v30
	v_max3_f32 v163, v163, v31, v64
	v_max3_f32 v163, v163, v65, v66
	v_max3_f32 v163, v163, v67, v68
	v_max3_f32 v163, v163, v69, v70
	v_max3_f32 v163, v163, v71, v72
	v_max3_f32 v163, v163, v73, v74
	v_max3_f32 v163, v163, v75, v76
	v_max3_f32 v163, v163, v77, v78
	v_max_f32_e32 v163, v163, v79
	ds_bpermute_b32 v210, v156, v163
	s_waitcnt lgkmcnt(0)
	v_max_f32_e32 v163, v163, v210
	v_frexp_exp_i32_f32_e32 v210, v163
	v_max_i32_e32 v210, 0, v210
	v_sub_u32_e32 v247, 0, v210
	v_ldexp_f32 v247, 1.0, v247
	v_cvt_f32_i32_e32 v210, v210
	v_mul_f32_e32 v149, v149, v247
	v_mul_f32_e32 v32, v32, v247
	v_mul_f32_e32 v33, v33, v247
	v_mul_f32_e32 v34, v34, v247
	v_mul_f32_e32 v35, v35, v247
	v_mul_f32_e32 v36, v36, v247
	v_mul_f32_e32 v37, v37, v247
	v_mul_f32_e32 v38, v38, v247
	v_mul_f32_e32 v39, v39, v247
	v_mul_f32_e32 v40, v40, v247
	v_mul_f32_e32 v41, v41, v247
	v_mul_f32_e32 v42, v42, v247
	v_mul_f32_e32 v43, v43, v247
	v_mul_f32_e32 v44, v44, v247
	v_mul_f32_e32 v45, v45, v247
	v_mul_f32_e32 v46, v46, v247
	v_mul_f32_e32 v47, v47, v247
	v_mul_f32_e32 v0, v0, v247
	v_mul_f32_e32 v1, v1, v247
	v_mul_f32_e32 v2, v2, v247
	v_mul_f32_e32 v3, v3, v247
	v_mul_f32_e32 v4, v4, v247
	v_mul_f32_e32 v5, v5, v247
	v_mul_f32_e32 v6, v6, v247
	v_mul_f32_e32 v7, v7, v247
	v_mul_f32_e32 v8, v8, v247
	v_mul_f32_e32 v9, v9, v247
	v_mul_f32_e32 v10, v10, v247
	v_mul_f32_e32 v11, v11, v247
	v_mul_f32_e32 v12, v12, v247
	v_mul_f32_e32 v13, v13, v247
	v_mul_f32_e32 v14, v14, v247
	v_mul_f32_e32 v15, v15, v247
	v_sub_f32_e32 v164, v164, v210
	v_sub_f32_e32 v165, v165, v210
	v_sub_f32_e32 v166, v166, v210
	v_sub_f32_e32 v167, v167, v210
	v_sub_f32_e32 v168, v168, v210
	v_sub_f32_e32 v169, v169, v210
	v_sub_f32_e32 v170, v170, v210
	v_sub_f32_e32 v171, v171, v210
	v_sub_f32_e32 v172, v172, v210
	v_sub_f32_e32 v173, v173, v210
	v_sub_f32_e32 v174, v174, v210
	v_sub_f32_e32 v175, v175, v210
	v_sub_f32_e32 v176, v176, v210
	v_sub_f32_e32 v177, v177, v210
	v_sub_f32_e32 v178, v178, v210
	v_sub_f32_e32 v179, v179, v210
	v_sub_f32_e32 v48, v48, v210
	v_sub_f32_e32 v49, v49, v210
	v_sub_f32_e32 v50, v50, v210
	v_sub_f32_e32 v51, v51, v210
	v_sub_f32_e32 v52, v52, v210
	v_sub_f32_e32 v53, v53, v210
	v_sub_f32_e32 v54, v54, v210
	v_sub_f32_e32 v55, v55, v210
	v_sub_f32_e32 v56, v56, v210
	v_sub_f32_e32 v57, v57, v210
	v_sub_f32_e32 v58, v58, v210
	v_sub_f32_e32 v59, v59, v210
	v_sub_f32_e32 v60, v60, v210
	v_sub_f32_e32 v61, v61, v210
	v_sub_f32_e32 v62, v62, v210
	v_sub_f32_e32 v63, v63, v210
	v_sub_f32_e32 v80, v80, v210
	v_sub_f32_e32 v81, v81, v210
	v_sub_f32_e32 v82, v82, v210
	v_sub_f32_e32 v83, v83, v210
	v_sub_f32_e32 v84, v84, v210
	v_sub_f32_e32 v85, v85, v210
	v_sub_f32_e32 v86, v86, v210
	v_sub_f32_e32 v87, v87, v210
	v_sub_f32_e32 v88, v88, v210
	v_sub_f32_e32 v89, v89, v210
	v_sub_f32_e32 v90, v90, v210
	v_sub_f32_e32 v91, v91, v210
	v_sub_f32_e32 v92, v92, v210
	v_sub_f32_e32 v93, v93, v210
	v_sub_f32_e32 v94, v94, v210
	v_sub_f32_e32 v95, v95, v210
	v_add_f32_e32 v162, v162, v210
	s_branch .Lmla1_post

; template <bool MLA, int DK, int DV>
; __device__ __forceinline__ void attn_core(const Params& p, int b, int h, int map, int q0, int nt, char* smem,
;                                           f32x16 (&o)[DV / 32], float& lout) {
;     ...
;           const float x_ = __builtin_amdgcn_exp2f(fmaf(cur_[e_ >> 4][e_ & 15], sc, -mrun));
;           cur_[e_ >> 4][e_ & 15] = x_; psum += x_;
;         }
;       }
;       __builtin_amdgcn_sched_group_barrier(0x100, NM, 0);
; #pragma unroll
;       for (int j = 0; j < NM; ++j) {
;         __builtin_amdgcn_sched_group_barrier(0x008, 1, 0);
;         __builtin_amdgcn_sched_group_barrier(0x002, 96 / NM, 0);
;       }
;     } else {
; #pragma unroll
;       for (int sub = 0; sub < 2; ++sub)
; #pragma unroll
;         for (int i = 0; i < 16; ++i) { const float x_ = __builtin_amdgcn_exp2f(fmaf(cur_[sub][i], sc, -mrun)); cur_[sub][i] = x_; psum += x_; }
;     }
;     lrun += psum;
;     bf16x8 pb[4];
; #pragma unroll
;     for (int kb = 0; kb < 4; ++kb) {
;       const int sub = kb >> 1, s8 = (kb & 1) * 8;
;       u32x4 pk;
;       pk.x = pack2(cur_[sub][s8 + 0], cur_[sub][s8 + 1]);
;       pk.y = pack2(cur_[sub][s8 + 2], cur_[sub][s8 + 3]);
;       pk.z = pack2(cur_[sub][s8 + 4], cur_[sub][s8 + 5]);
;       pk.w = pack2(cur_[sub][s8 + 6], cur_[sub][s8 + 7]);
;       pb[kb] = __builtin_bit_cast(bf16x8, pk);
;     }
;     float mx = -INFINITY;
; #pragma unroll
;     for (int hb = 0; hb < 2; ++hb) {
;       bf16x8 vf[2][NDVT];
; #pragma unroll
;       for (int q = 0; q < 2; ++q)
; #pragma unroll
;         for (int d = 0; d < NDVT; ++d) {
;           const bft* vp = Vc + (d * 32 + r) * VS_STRIDE + (hb * 2 + q) * 16 + 4 * h2;
;           const u32x2 lo = *(const u32x2*)vp, hi = *(const u32x2*)(vp + 8);
;           const u32x4 pa4 = {lo.x, lo.y, hi.x, hi.y};
;           vf[q][d] = __builtin_bit_cast(bf16x8, pa4);
;         }
; #pragma unroll
;       for (int q = 0; q < 2; ++q) {
;         const int kb = hb * 2 + q;
; #pragma unroll
;         for (int d = 0; d < NDVT; ++d) o[d] = MFMA32(vf[q][d], pb[kb], o[d]);
; #pragma unroll
;         for (int i = 0; i < 8; ++i) mx = fmaxf(mx, nxt_[kb >> 1][(kb & 1) * 8 + i]);
;       }
;     }
;     if (has1) {
;       mx *= sc;
;       if (__any(mx > mrun + 12.f)) {
;         mx = fmaxf(mx, __shfl_xor(mx, 32));
;         const float mnew = fmaxf(mrun, mx);
.Lm2i_d:
	s_or_b64 exec, exec, s[74:75]
	ds_read2_b64 v[202:205], v245 offset0:100 offset1:102
	v_exp_f32_e32 v81, v81
	v_exp_f32_e32 v82, v82
	s_waitcnt lgkmcnt(5)
	v_mfma_f32_32x32x16_bf16 v[64:79], v[248:251], v[112:115], v[64:79]
	ds_read2_b64 v[248:251], v244 offset0:72 offset1:74
	v_exp_f32_e32 v83, v83
	v_add_f32_e32 v163, v80, v163
	v_add_f32_e32 v210, v81, v210
	s_waitcnt lgkmcnt(5)
	v_mfma_f32_32x32x16_bf16 v[64:79], v[216:219], v[116:119], v[64:79]
	ds_read2_b64 v[216:219], v245 offset0:104 offset1:106
	v_add_f32_e32 v163, v82, v163
	v_add_f32_e32 v210, v83, v210
	v_exp_f32_e32 v84, v84
	v_exp_f32_e32 v85, v85
	s_waitcnt lgkmcnt(5)
	v_mfma_f32_32x32x16_bf16 v[32:47], v[132:135], v[180:183], v[32:47]
	ds_read2_b64 v[132:135], v244 offset0:76 offset1:78
	v_exp_f32_e32 v86, v86
	v_exp_f32_e32 v87, v87
	s_waitcnt lgkmcnt(5)
	v_mfma_f32_32x32x16_bf16 v[0:15], v[136:139], v[180:183], v[0:15]
	ds_read2_b64 v[136:139], v245 offset0:108 offset1:110
	v_add_f32_e32 v163, v84, v163
	v_add_f32_e32 v210, v85, v210
	v_add_f32_e32 v163, v86, v163
	v_add_f32_e32 v210, v87, v210
	v_cvt_pk_bf16_f32 v188, v80, v81
	s_waitcnt lgkmcnt(5)
	v_mfma_f32_32x32x16_bf16 v[32:47], v[198:201], v[184:187], v[32:47]
	v_cvt_pk_bf16_f32 v189, v82, v83
	v_cvt_pk_bf16_f32 v190, v84, v85
	v_cvt_pk_bf16_f32 v191, v86, v87
	v_exp_f32_e32 v88, v88
	s_waitcnt lgkmcnt(4)
	v_mfma_f32_32x32x16_bf16 v[0:15], v[202:205], v[184:187], v[0:15]
	v_exp_f32_e32 v89, v89
	v_exp_f32_e32 v90, v90
	v_exp_f32_e32 v91, v91
	s_waitcnt lgkmcnt(3)
	v_mfma_f32_32x32x16_bf16 v[32:47], v[248:251], v[188:191], v[32:47]
	v_add_f32_e32 v163, v88, v163
	v_add_f32_e32 v210, v89, v210
	v_add_f32_e32 v163, v90, v163
	v_add_f32_e32 v210, v91, v210
	s_waitcnt lgkmcnt(2)
	v_mfma_f32_32x32x16_bf16 v[0:15], v[216:219], v[188:191], v[0:15]
	v_exp_f32_e32 v92, v92
	v_exp_f32_e32 v93, v93
	v_exp_f32_e32 v94, v94
	v_exp_f32_e32 v95, v95
	v_add_f32_e32 v163, v92, v163
	v_add_f32_e32 v210, v93, v210
	v_add_f32_e32 v163, v94, v163
	v_add_f32_e32 v210, v95, v210
	v_cvt_pk_bf16_f32 v192, v88, v89
	v_cvt_pk_bf16_f32 v193, v90, v91
	v_cvt_pk_bf16_f32 v194, v92, v93
	v_cvt_pk_bf16_f32 v195, v94, v95
	s_waitcnt lgkmcnt(1)
	s_nop 0
	v_mfma_f32_32x32x16_bf16 v[32:47], v[132:135], v[192:195], v[32:47]
	s_waitcnt lgkmcnt(0)
	v_mfma_f32_32x32x16_bf16 v[0:15], v[136:139], v[192:195], v[0:15]
	v_add_f32_e32 v163, v163, v210
	v_add_f32_e32 v149, v149, v163
	v_cmp_lt_f32_e32 vcc, 0x45800000, v163
	s_cbranch_vccz .Lmla2_post
	v_max3_f32 v163, v48, v49, v50
	v_max3_f32 v163, v163, v51, v52
	v_max3_f32 v163, v163, v53, v54
	v_max3_f32 v163, v163, v55, v56
	v_max3_f32 v163, v163, v57, v58
	v_max3_f32 v163, v163, v59, v60
	v_max3_f32 v163, v163, v61, v62
	v_max3_f32 v163, v163, v63, v80
	v_max3_f32 v163, v163, v81, v82
	v_max3_f32 v163, v163, v83, v84
	v_max3_f32 v163, v163, v85, v86
	v_max3_f32 v163, v163, v87, v88
	v_max3_f32 v163, v163, v89, v90
	v_max3_f32 v163, v163, v91, v92
	v_max3_f32 v163, v163, v93, v94
	v_max_f32_e32 v163, v163, v95
	ds_bpermute_b32 v210, v156, v163
	s_waitcnt lgkmcnt(0)
	v_max_f32_e32 v163, v163, v210
	v_frexp_exp_i32_f32_e32 v210, v163
	v_max_i32_e32 v210, 0, v210
	v_sub_u32_e32 v247, 0, v210
	v_ldexp_f32 v247, 1.0, v247
	v_cvt_f32_i32_e32 v210, v210
	v_mul_f32_e32 v149, v149, v247
	v_mul_f32_e32 v32, v32, v247
	v_mul_f32_e32 v33, v33, v247
	v_mul_f32_e32 v34, v34, v247
	v_mul_f32_e32 v35, v35, v247
	v_mul_f32_e32 v36, v36, v247
	v_mul_f32_e32 v37, v37, v247
	v_mul_f32_e32 v38, v38, v247
	v_mul_f32_e32 v39, v39, v247
	v_mul_f32_e32 v40, v40, v247
	v_mul_f32_e32 v41, v41, v247
	v_mul_f32_e32 v42, v42, v247
	v_mul_f32_e32 v43, v43, v247
	v_mul_f32_e32 v44, v44, v247
	v_mul_f32_e32 v45, v45, v247
	v_mul_f32_e32 v46, v46, v247
	v_mul_f32_e32 v47, v47, v247
	v_mul_f32_e32 v0, v0, v247
	v_mul_f32_e32 v1, v1, v247
	v_mul_f32_e32 v2, v2, v247
	v_mul_f32_e32 v3, v3, v247
	v_mul_f32_e32 v4, v4, v247
	v_mul_f32_e32 v5, v5, v247
	v_mul_f32_e32 v6, v6, v247
	v_mul_f32_e32 v7, v7, v247
	v_mul_f32_e32 v8, v8, v247
	v_mul_f32_e32 v9, v9, v247
	v_mul_f32_e32 v10, v10, v247
	v_mul_f32_e32 v11, v11, v247
	v_mul_f32_e32 v12, v12, v247
	v_mul_f32_e32 v13, v13, v247
	v_mul_f32_e32 v14, v14, v247
	v_mul_f32_e32 v15, v15, v247
	v_sub_f32_e32 v164, v164, v210
	v_sub_f32_e32 v165, v165, v210
	v_sub_f32_e32 v166, v166, v210
	v_sub_f32_e32 v167, v167, v210
	v_sub_f32_e32 v168, v168, v210
	v_sub_f32_e32 v169, v169, v210
	v_sub_f32_e32 v170, v170, v210
	v_sub_f32_e32 v171, v171, v210
	v_sub_f32_e32 v172, v172, v210
	v_sub_f32_e32 v173, v173, v210
	v_sub_f32_e32 v174, v174, v210
	v_sub_f32_e32 v175, v175, v210
	v_sub_f32_e32 v176, v176, v210
	v_sub_f32_e32 v177, v177, v210
	v_sub_f32_e32 v178, v178, v210
	v_sub_f32_e32 v179, v179, v210
	v_sub_f32_e32 v16, v16, v210
	v_sub_f32_e32 v17, v17, v210
	v_sub_f32_e32 v18, v18, v210
	v_sub_f32_e32 v19, v19, v210
	v_sub_f32_e32 v20, v20, v210
	v_sub_f32_e32 v21, v21, v210
	v_sub_f32_e32 v22, v22, v210
	v_sub_f32_e32 v23, v23, v210
	v_sub_f32_e32 v24, v24, v210
	v_sub_f32_e32 v25, v25, v210
	v_sub_f32_e32 v26, v26, v210
	v_sub_f32_e32 v27, v27, v210
	v_sub_f32_e32 v28, v28, v210
	v_sub_f32_e32 v29, v29, v210
	v_sub_f32_e32 v30, v30, v210
	v_sub_f32_e32 v31, v31, v210
	v_sub_f32_e32 v64, v64, v210
	v_sub_f32_e32 v65, v65, v210
	v_sub_f32_e32 v66, v66, v210
	v_sub_f32_e32 v67, v67, v210
	v_sub_f32_e32 v68, v68, v210
	v_sub_f32_e32 v69, v69, v210
	v_sub_f32_e32 v70, v70, v210
	v_sub_f32_e32 v71, v71, v210
	v_sub_f32_e32 v72, v72, v210
	v_sub_f32_e32 v73, v73, v210
	v_sub_f32_e32 v74, v74, v210
	v_sub_f32_e32 v75, v75, v210
	v_sub_f32_e32 v76, v76, v210
	v_sub_f32_e32 v77, v77, v210
	v_sub_f32_e32 v78, v78, v210
	v_sub_f32_e32 v79, v79, v210
	v_add_f32_e32 v162, v162, v210
	s_branch .Lmla2_post
